# C loop: staging ds_writes moved into the first half-tile slot (no LDS-write wait before the barrier); per-layer gain-max scan replaced by one 64-lane load plus ds_swizzle max reduction
# baseline (speedup 1.0000x reference)
; #define LAS __attribute__((address_space(3)))
; __device__ __forceinline__ void attn_phase(CP P, LAS unsigned char* lds, int layer) {
;     const bf16_t* proj = (const bf16_t*)(P->ws + WS_PROJ); const bf16_t* vt = (const bf16_t*)(P->ws + WS_VT); bf16_t* obuf = (bf16_t*)(P->ws + WS_O);
;     const int G = gridDim.x;
;     unsigned long long* sgA = (unsigned long long*)(P->ws + WS_SG) + (size_t)(3 * layer) * MTOK; unsigned long long* sgB = sgA + MTOK; unsigned long long* sgC = sgB + MTOK;
;     {
;         float gq = 0.f, gk = 0.f;
;         for (int d = 0; d < 64; ++d) { gq = fmaxf(gq, fabsf(P->c_q_gain[layer * 64 + d])); gk = fmaxf(gk, fabsf(P->c_k_gain[layer * 64 + d])); }
;         const float bound = 64.f * C2 * gq * gk;
;         if (bound < 60.f) {
.LBB0_192:
	s_or_b64 exec, exec, s[4:5]
	v_readlane_b32 s8, v250, 11
	v_readlane_b32 s9, v250, 12
	s_waitcnt lgkmcnt(0)
	s_barrier
	s_load_dwordx4 s[12:15], s[8:9], 0x30
	s_load_dwordx2 s[82:83], s[8:9], 0x88
	s_mov_b64 s[4:5], 0
	v_mov_b32_e32 v0, 0
	v_mov_b32_e32 v1, 0
	s_waitcnt lgkmcnt(0)
	s_add_u32 s6, s12, s72
	s_addc_u32 s7, s13, s73
	s_add_u32 s10, s14, s72
	s_addc_u32 s11, s15, s73
	v_and_b32_e32 v2, 63, v199
	v_lshlrev_b32_e32 v2, 2, v2
	global_load_dword v3, v2, s[6:7]
	global_load_dword v4, v2, s[10:11]
	s_waitcnt vmcnt(0)
	v_and_b32_e32 v3, 0x7fffffff, v3
	v_and_b32_e32 v4, 0x7fffffff, v4
	ds_swizzle_b32 v5, v3 offset:0x041f
	ds_swizzle_b32 v6, v4 offset:0x041f
	s_waitcnt lgkmcnt(0)
	v_max_f32_e32 v3, v3, v5
	v_max_f32_e32 v4, v4, v6
	ds_swizzle_b32 v5, v3 offset:0x081f
	ds_swizzle_b32 v6, v4 offset:0x081f
	s_waitcnt lgkmcnt(0)
	v_max_f32_e32 v3, v3, v5
	v_max_f32_e32 v4, v4, v6
	ds_swizzle_b32 v5, v3 offset:0x101f
	ds_swizzle_b32 v6, v4 offset:0x101f
	s_waitcnt lgkmcnt(0)
	v_max_f32_e32 v3, v3, v5
	v_max_f32_e32 v4, v4, v6
	ds_swizzle_b32 v5, v3 offset:0x201f
	ds_swizzle_b32 v6, v4 offset:0x201f
	s_waitcnt lgkmcnt(0)
	v_max_f32_e32 v3, v3, v5
	v_max_f32_e32 v4, v4, v6
	ds_swizzle_b32 v5, v3 offset:0x401f
	ds_swizzle_b32 v6, v4 offset:0x401f
	s_waitcnt lgkmcnt(0)
	v_max_f32_e32 v3, v3, v5
	v_max_f32_e32 v4, v4, v6
	s_nop 1
	v_readlane_b32 s4, v3, 0
	v_readlane_b32 s5, v3, 32
	v_readlane_b32 s12, v4, 0
	v_readlane_b32 s13, v4, 32
	s_nop 3
	v_mov_b32_e32 v1, s4
	v_mov_b32_e32 v0, s12
	v_max_f32_e32 v1, s5, v1
	v_max_f32_e32 v0, s13, v0
	s_mul_i32 s4, s74, 0x60000
	s_add_u32 s4, s82, s4
	s_addc_u32 s5, s83, 0
	s_add_u32 s38, s4, 0x2b120000
	s_addc_u32 s39, s5, 0
	s_add_u32 s84, s82, 0x21400000
	s_addc_u32 s85, s83, 0
	s_add_u32 s86, s82, 0x19c00000
	s_addc_u32 s87, s83, 0
	s_add_u32 s88, s82, 0x23000000
	s_addc_u32 s89, s83, 0
	v_mul_f32_e32 v1, 0x4138aa3b, v1
	s_add_u32 s20, s4, 0x2b160000
	v_mul_f32_e32 v0, v0, v1
	s_mov_b32 s4, 0x42700000
	v_cmp_ngt_f32_e32 vcc, s4, v0
	s_addc_u32 s21, s5, 0
	s_cbranch_vccz .LBB0_202
	v_readlane_b32 s4, v250, 5
	v_readlane_b32 s5, v250, 6
	s_andn2_b64 vcc, exec, s[4:5]
	s_cbranch_vccnz .LBB0_203
	s_add_u32 s4, s82, 0x21400080
	s_addc_u32 s5, s83, 0
	s_add_u32 s6, s82, 0x19c79a00
	s_addc_u32 s7, s83, 0
	s_mov_b32 s14, s2
	s_mov_b32 s15, s2
	s_branch .LBB0_198

; __device__ __forceinline__ void attn_c_unit(LAS unsigned char* lds, const bf16_t* proj, const bf16_t* vt, bf16_t* obuf, int b, int hk, int blk, float mref, unsigned long long* sg) {
;     ...
;         const int buf = it & 3;
;         if (it + 2 < nT) { kreg = *(const u32x4*)(kg + (size_t)((it + 2) * 64) * INW); vreg = *(const u32x4*)(vg + (it + 2) * 64); }
;         const LAS unsigned char* kb = lds + CK + buf * ATT_TILE + pr * KP + 16 * h;
;         f32x16 s00, s01, s10, s11;
;         {
;             const bf16x8 a0 = *(const LAS bf16x8*)(kb), a1 = *(const LAS bf16x8*)(kb + 32 * KP);
;             s00 = __builtin_amdgcn_mfma_f32_32x32x16_bf16(a0, qf[0][0], negm, 0, 0, 0);
;             s10 = __builtin_amdgcn_mfma_f32_32x32x16_bf16(a0, qf[1][0], negm, 0, 0, 0);
;             s01 = __builtin_amdgcn_mfma_f32_32x32x16_bf16(a1, qf[0][0], negm, 0, 0, 0);
;             s11 = __builtin_amdgcn_mfma_f32_32x32x16_bf16(a1, qf[1][0], negm, 0, 0, 0);
;         }
; #pragma unroll
;         for (int ks = 1; ks < 4; ++ks) {
;             const bf16x8 a0 = *(const LAS bf16x8*)(kb + 32 * ks), a1 = *(const LAS bf16x8*)(kb + 32 * KP + 32 * ks);
;             s00 = __builtin_amdgcn_mfma_f32_32x32x16_bf16(a0, qf[0][ks], s00, 0, 0, 0);
;             s10 = __builtin_amdgcn_mfma_f32_32x32x16_bf16(a0, qf[1][ks], s10, 0, 0, 0);
;             s01 = __builtin_amdgcn_mfma_f32_32x32x16_bf16(a1, qf[0][ks], s01, 0, 0, 0);
;             s11 = __builtin_amdgcn_mfma_f32_32x32x16_bf16(a1, qf[1][ks], s11, 0, 0, 0);
;         }
;         u32x4 pw0[4], pw1[4];
;         {
;             float ps = 0.f;
; #pragma unroll
;             for (int i = 0; i < 16; ++i) { s00[i] = __builtin_amdgcn_exp2f(s00[i]); s01[i] = __builtin_amdgcn_exp2f(s01[i]); ps += s00[i] + s01[i]; }
;             l0 += ps;
; #pragma unroll
;             for (int q = 0; q < 4; ++q) { pw0[0][q] = pk_bf16(s00[2 * q], s00[2 * q + 1]); pw0[1][q] = pk_bf16(s00[8 + 2 * q], s00[8 + 2 * q + 1]);
;                                           pw0[2][q] = pk_bf16(s01[2 * q], s01[2 * q + 1]); pw0[3][q] = pk_bf16(s01[8 + 2 * q], s01[8 + 2 * q + 1]); }
;         }
;         {
;             float ps = 0.f;
; #pragma unroll
;             for (int i = 0; i < 16; ++i) { s10[i] = __builtin_amdgcn_exp2f(s10[i]); s11[i] = __builtin_amdgcn_exp2f(s11[i]); ps += s10[i] + s11[i]; }
;             l1 += ps;
; #pragma unroll
.Lc_noload:
	s_and_b32 s23, s22, 3
	s_mulk_i32 s23, 0x2400
	v_add_u32_e32 v128, s23, v198
	ds_read_b128 v[226:229], v128 offset:4608
	ds_read_b128 v[230:233], v128 offset:4640
	ds_read_b128 v[234:237], v128 offset:4672
	ds_read_b128 v[238:241], v128 offset:4704
	s_and_b32 s24, s22, 7
	s_mulk_i32 s24, 0x2400
	v_add_u32_e32 v246, s24, v200
	s_waitcnt lgkmcnt(4)
	v_mfma_f32_32x32x16_bf16 v[32:47], v[202:205], v[96:99], v[32:47]
	v_exp_f32_e32 v64, v64
	v_exp_f32_e32 v65, v65
	v_exp_f32_e32 v66, v66
	v_exp_f32_e32 v67, v67
	v_add_f32_e32 v190, v190, v64
	v_mfma_f32_32x32x16_bf16 v[0:15], v[202:205], v[112:115], v[0:15]
	v_add_f32_e32 v214, v214, v65
	v_cvt_pk_bf16_f32 v64, v64, v65
	v_exp_f32_e32 v68, v68
	v_exp_f32_e32 v69, v69
	v_add_f32_e32 v190, v190, v66
	v_mfma_f32_32x32x16_bf16 v[48:63], v[192:195], v[96:99], v[48:63]
	v_add_f32_e32 v214, v214, v67
	v_cvt_pk_bf16_f32 v65, v66, v67
	v_exp_f32_e32 v70, v70
	v_exp_f32_e32 v71, v71
	v_add_f32_e32 v190, v190, v68
	v_mfma_f32_32x32x16_bf16 v[16:31], v[192:195], v[112:115], v[16:31]
	v_add_f32_e32 v214, v214, v69
	v_cvt_pk_bf16_f32 v66, v68, v69
	v_exp_f32_e32 v72, v72
	v_exp_f32_e32 v73, v73
	v_add_f32_e32 v190, v190, v70
	v_mfma_f32_32x32x16_bf16 v[32:47], v[210:213], v[100:103], v[32:47]
	v_add_f32_e32 v214, v214, v71
	v_cvt_pk_bf16_f32 v67, v70, v71
	v_exp_f32_e32 v74, v74
	v_exp_f32_e32 v75, v75
	v_add_f32_e32 v190, v190, v72
	v_mfma_f32_32x32x16_bf16 v[0:15], v[210:213], v[116:119], v[0:15]
	v_add_f32_e32 v214, v214, v73
	v_cvt_pk_bf16_f32 v68, v72, v73
	v_exp_f32_e32 v76, v76
	v_exp_f32_e32 v77, v77
	v_add_f32_e32 v190, v190, v74
	v_mfma_f32_32x32x16_bf16 v[48:63], v[242:245], v[100:103], v[48:63]
	v_add_f32_e32 v214, v214, v75
	v_cvt_pk_bf16_f32 v69, v74, v75
	v_exp_f32_e32 v78, v78
	v_exp_f32_e32 v79, v79
	v_add_f32_e32 v190, v190, v76
	v_mfma_f32_32x32x16_bf16 v[16:31], v[242:245], v[116:119], v[16:31]
	ds_read_b128 v[202:205], v246 offset:36864
	ds_read_b128 v[192:195], v246 offset:41472
	ds_read_b128 v[210:213], v246 offset:36896
	ds_read_b128 v[242:245], v246 offset:41504
	s_waitcnt lgkmcnt(4)
	s_cmpk_gt_u32 s22, 0x7d
	s_cbranch_scc1 .Lc_nostore
	s_xor_b32 s23, s23, 0x4800
	v_add_u32_e32 v201, s23, v197
	s_add_i32 s23, s22, 2
	s_and_b32 s23, s23, 7
	s_mulk_i32 s23, 0x2400
	v_add_u32_e32 v206, s23, v197
	s_waitcnt vmcnt(0)
	ds_write_b128 v201, v[130:133]
	ds_write_b128 v206, v[134:137] offset:36864
.Lc_nostore:
	v_add_f32_e32 v214, v214, v77
	v_cvt_pk_bf16_f32 v70, v76, v77
	v_add_f32_e32 v190, v190, v78
	v_add_f32_e32 v214, v214, v79
	v_cvt_pk_bf16_f32 v71, v78, v79
	v_mfma_f32_32x32x16_bf16 v[96:111], v[226:229], v[146:149], 0
	v_exp_f32_e32 v80, v80
	v_exp_f32_e32 v81, v81
	v_exp_f32_e32 v82, v82
	v_exp_f32_e32 v83, v83
	v_add_f32_e32 v191, v191, v80
	v_mfma_f32_32x32x16_bf16 v[112:127], v[226:229], v[154:157], 0
	v_add_f32_e32 v215, v215, v81
	v_cvt_pk_bf16_f32 v80, v80, v81
	v_exp_f32_e32 v84, v84
	v_exp_f32_e32 v85, v85
	v_add_f32_e32 v191, v191, v82
	v_mfma_f32_32x32x16_bf16 v[96:111], v[230:233], v[138:141], v[96:111]
	v_add_f32_e32 v215, v215, v83
	v_cvt_pk_bf16_f32 v81, v82, v83
	v_exp_f32_e32 v86, v86
	v_exp_f32_e32 v87, v87
	v_add_f32_e32 v191, v191, v84
	v_mfma_f32_32x32x16_bf16 v[112:127], v[230:233], v[158:161], v[112:127]
	v_add_f32_e32 v215, v215, v85
	v_cvt_pk_bf16_f32 v82, v84, v85
	v_exp_f32_e32 v88, v88
	v_exp_f32_e32 v89, v89
	v_add_f32_e32 v191, v191, v86
	v_mfma_f32_32x32x16_bf16 v[96:111], v[234:237], v[142:145], v[96:111]
	v_add_f32_e32 v215, v215, v87
	v_cvt_pk_bf16_f32 v83, v86, v87
	v_exp_f32_e32 v90, v90
	v_exp_f32_e32 v91, v91
	v_add_f32_e32 v191, v191, v88
	v_mfma_f32_32x32x16_bf16 v[112:127], v[234:237], v[162:165], v[112:127]
	v_add_f32_e32 v215, v215, v89
	v_cvt_pk_bf16_f32 v84, v88, v89
	v_exp_f32_e32 v92, v92
	v_exp_f32_e32 v93, v93
	v_add_f32_e32 v191, v191, v90
	v_mfma_f32_32x32x16_bf16 v[96:111], v[238:241], v[150:153], v[96:111]
	v_add_f32_e32 v215, v215, v91
	v_cvt_pk_bf16_f32 v85, v90, v91
	v_exp_f32_e32 v94, v94
	v_exp_f32_e32 v95, v95
	v_add_f32_e32 v191, v191, v92
	v_mfma_f32_32x32x16_bf16 v[112:127], v[238:241], v[166:169], v[112:127]
	v_add_f32_e32 v215, v215, v93
	v_cvt_pk_bf16_f32 v86, v92, v93
	v_add_f32_e32 v191, v191, v94
	v_add_f32_e32 v215, v215, v95
	v_cvt_pk_bf16_f32 v87, v94, v95
	s_bitcmp0_b32 s22, 0
	s_cbranch_scc1 .Lc_nobar
	s_waitcnt lgkmcnt(0)
	s_barrier
